# v15 plus P0 item split: idle (non-adaLN) workgroups take 3 exclusive transposes items instead of 4, now that the adaLN path is short
# baseline (speedup 1.0000x reference)
; __device__ __forceinline__ void p0_prologue(const Args& a, LAS unsigned char* lds, int tid, int wid, int lane, int G) {
;     ...
;     constexpr int I_IN = 32 * 256, I_SQ = 32 * 32, NITEMS = I_IN + 3 * I_SQ;
;     const int nfree = G > 192 ? G - 192 : 0, E = nfree * 8 * 4 < NITEMS ? nfree * 8 * 4 : NITEMS;
;     const bool isfree = (int)blockIdx.x >= 192;
;     for (int it = isfree ? ((int)blockIdx.x - 192) * 8 + wid : E + gw; it < NITEMS; ) {
;         int r = it;
;         it = (it < E) ? ((it + nfree * 8 < E) ? it + nfree * 8 : E + gw) : it + NGW;
.LBB0_46:
	s_lshl_b32 s0, s2, 3
	s_add_i32 s93, s92, s0
	s_max_i32 s0, s30, 0xc0
	s_lshl_b32 s3, s0, 3
	s_addk_i32 s3, 0xfa00
	s_min_i32 s0, s3, 0xb00
	s_mul_i32 s6, s0, 3
	s_lshl_b32 s96, s30, 3
	s_add_i32 s0, s93, 0xfffffa00
	s_add_i32 s7, s6, s93
	s_cmpk_gt_i32 s2, 0xbf
	s_cselect_b32 s8, s0, s7
	s_cmpk_gt_i32 s8, 0x2bff
	s_cbranch_scc1 .LBB0_69
	v_lshlrev_b32_e32 v0, 3, v176
	v_and_b32_e32 v0, 56, v0
	v_mul_u32_u24_e32 v2, 0x104, v0
	v_lshlrev_b32_e32 v0, 1, v0
	v_mov_b32_e32 v1, 0
	s_mul_i32 s0, s92, 0x4100
	v_lshrrev_b32_e32 v11, 3, v177
	v_lshl_add_u64 v[6:7], s[28:29], 0, v[0:1]
	s_mov_b64 s[4:5], 0x5300000
	s_add_i32 s0, s0, 0
	v_lshl_add_u64 v[0:1], v[6:7], 0, s[4:5]
	v_lshlrev_b32_e32 v3, 2, v11
	s_mov_b64 s[4:5], 0x4b00000
	v_add3_u32 v12, s0, v2, v3
	v_lshl_add_u64 v[2:3], v[6:7], 0, s[4:5]
	s_mov_b64 s[4:5], 0x4300000
	v_lshl_add_u64 v[4:5], v[6:7], 0, s[4:5]
	v_lshlrev_b32_e32 v8, 6, v176
	s_mov_b64 s[4:5], 0x9b00000
	s_mov_b32 s1, 0
	v_lshl_add_u32 v10, v177, 2, s0
	v_or_b32_e32 v13, 8, v11
	v_or_b32_e32 v14, 16, v11
	v_or_b32_e32 v15, 24, v11
	v_or_b32_e32 v16, 32, v11
	v_or_b32_e32 v17, 40, v11
	v_or_b32_e32 v18, 48, v11
	v_or_b32_e32 v19, 56, v11
	v_and_b32_e32 v20, 64, v8
	v_lshl_add_u64 v[6:7], v[6:7], 0, s[4:5]
	s_movk_i32 s9, 0xfff
	v_add_u32_e32 v21, 0x400, v12
	s_branch .LBB0_49
